# attention block selection rewritten by hand: branch-free integer rank counting (v_cmp + v_addc), DPP or-reduce instead of 116 exec-masked compare blocks
# speedup vs baseline: 1.0334x; 1.0096x over previous
.LBB0_176:
	s_or_b64 exec, exec, s[0:1]
	v_add_f32_e32 v0, 0, v65
	v_add_f32_e32 v0, v0, v64
	v_add_f32_e32 v0, v0, v49
	v_add_f32_e32 v0, v0, v48
	v_add_f32_e32 v0, v0, v51
	v_add_f32_e32 v0, v0, v50
	v_add_f32_e32 v0, v0, v53
	v_add_f32_e32 v0, v0, v52
	v_add_f32_e32 v0, v0, v55
	v_add_f32_e32 v0, v0, v54
	v_add_f32_e32 v0, v0, v57
	v_add_f32_e32 v0, v0, v56
	v_add_f32_e32 v0, v0, v59
	v_add_f32_e32 v0, v0, v58
	v_add_f32_e32 v0, v0, v61
	v_add_f32_e32 v0, v0, v60
	v_add_f32_e32 v0, v0, v63
	v_add_f32_e32 v0, v0, v62
	v_add_f32_e32 v0, v0, v33
	v_add_f32_e32 v0, v0, v32
	v_add_f32_e32 v0, v0, v35
	v_add_f32_e32 v0, v0, v34
	v_add_f32_e32 v0, v0, v37
	v_add_f32_e32 v0, v0, v36
	v_add_f32_e32 v0, v0, v39
	v_add_f32_e32 v0, v0, v38
	v_add_f32_e32 v0, v0, v41
	v_add_f32_e32 v0, v0, v40
	v_add_f32_e32 v0, v0, v67
	v_add_f32_e32 v0, v0, v43
	v_add_f32_e32 v0, v0, v69
	v_add_f32_e32 v0, v0, v68
	v_add_f32_e32 v0, v0, v44
	v_add_f32_e32 v0, v0, v42
	v_add_f32_e32 v0, v0, v46
	v_add_f32_e32 v0, v0, v45
	v_add_f32_e32 v0, v0, v70
	v_add_f32_e32 v0, v0, v47
	v_add_f32_e32 v0, v0, v72
	v_add_f32_e32 v0, v0, v71
	v_add_f32_e32 v0, v0, v74
	v_add_f32_e32 v0, v0, v73
	v_add_f32_e32 v0, v0, v76
	v_add_f32_e32 v0, v0, v75
	v_add_f32_e32 v0, v0, v78
	v_add_f32_e32 v0, v0, v77
	v_add_f32_e32 v0, v0, v80
	v_add_f32_e32 v0, v0, v79
	v_add_f32_e32 v0, v0, v82
	v_add_f32_e32 v0, v0, v81
	v_add_f32_e32 v0, v0, v84
	v_add_f32_e32 v0, v0, v83
	v_add_f32_e32 v0, v0, v86
	v_add_f32_e32 v0, v0, v85
	v_add_f32_e32 v0, v0, v88
	v_add_f32_e32 v0, v0, v87
	v_add_f32_e32 v0, v0, v90
	v_add_f32_e32 v0, v0, v89
	v_add_f32_e32 v0, v0, v92
	v_add_f32_e32 v0, v0, v91
	v_add_f32_e32 v0, v0, v94
	v_add_f32_e32 v0, v0, v93
	v_add_f32_e32 v0, v0, v130
	v_add_f32_e32 v0, v0, v95
	ds_bpermute_b32 v1, v163, v0
	v_mul_f32_e32 v2, 0.5, v48
	ds_bpermute_b32 v2, v163, v2
	v_readlane_b32 s4, v251, 42
	v_readlane_b32 s5, v251, 43
	s_waitcnt lgkmcnt(1)
	v_add_f32_e32 v0, v0, v1
	v_div_scale_f32 v1, s[0:1], v0, v0, 1.0
	v_rcp_f32_e32 v3, v1
	v_div_scale_f32 v4, vcc, 1.0, v0, 1.0
	s_lshl_b32 s0, s2, 1
	v_fma_f32 v5, -v1, v3, 1.0
	v_fmac_f32_e32 v3, v5, v3
	v_mul_f32_e32 v5, v4, v3
	v_fma_f32 v6, -v1, v5, v4
	v_fmac_f32_e32 v5, v6, v3
	v_fma_f32 v1, -v1, v5, v4
	v_div_fmas_f32 v1, v1, v3, v5
	v_div_fixup_f32 v1, v1, v0, 1.0
	v_cmp_lt_f32_e32 vcc, 0, v0
	v_add_f32_e32 v0, v65, v64
	v_add_f32_e32 v3, v51, v50
	v_cndmask_b32_e32 v66, 0, v1, vcc
	v_fma_f32 v1, 0.5, v48, v49
	v_add_f32_e32 v0, v0, v1
	s_waitcnt lgkmcnt(0)
	v_cndmask_b32_e64 v1, v2, 0, s[4:5]
	v_add_f32_e32 v0, v0, v1
	v_mul_f32_e32 v1, 0.5, v52
	ds_bpermute_b32 v1, v163, v1
	v_fma_f32 v4, 0.5, v52, v53
	v_add_f32_e32 v3, v3, v4
	v_mul_f32_e32 v0, v66, v0
	v_fma_f32 v4, 0.5, v60, v61
	s_waitcnt lgkmcnt(0)
	v_cndmask_b32_e64 v2, v1, v2, s[4:5]
	v_add_f32_e32 v2, v3, v2
	v_mul_f32_e32 v3, 0.5, v56
	ds_bpermute_b32 v3, v163, v3
	v_mul_f32_e32 v2, v66, v2
	ds_write2_b32 v239, v0, v2 offset1:2
	v_add_f32_e32 v0, v55, v54
	v_fma_f32 v2, 0.5, v56, v57
	v_add_f32_e32 v0, v0, v2
	s_waitcnt lgkmcnt(1)
	v_cndmask_b32_e64 v1, v3, v1, s[4:5]
	v_add_f32_e32 v0, v0, v1
	v_mul_f32_e32 v1, 0.5, v60
	ds_bpermute_b32 v1, v163, v1
	v_add_f32_e32 v2, v59, v58
	v_add_f32_e32 v2, v2, v4
	v_mul_f32_e32 v0, v66, v0
	v_fma_f32 v4, 0.5, v36, v37
	s_waitcnt lgkmcnt(0)
	v_cndmask_b32_e64 v3, v1, v3, s[4:5]
	v_add_f32_e32 v2, v2, v3
	v_mul_f32_e32 v3, 0.5, v32
	ds_bpermute_b32 v3, v163, v3
	v_mul_f32_e32 v2, v66, v2
	ds_write2_b32 v239, v0, v2 offset0:4 offset1:6
	v_add_f32_e32 v0, v63, v62
	v_fma_f32 v2, 0.5, v32, v33
	v_add_f32_e32 v0, v0, v2
	s_waitcnt lgkmcnt(1)
	v_cndmask_b32_e64 v1, v3, v1, s[4:5]
	v_add_f32_e32 v0, v0, v1
	v_mul_f32_e32 v1, 0.5, v36
	ds_bpermute_b32 v1, v163, v1
	v_add_f32_e32 v2, v35, v34
	v_add_f32_e32 v2, v2, v4
	v_readlane_b32 s2, v252, 62
	v_mul_f32_e32 v0, v66, v0
	s_waitcnt lgkmcnt(0)
	v_cndmask_b32_e64 v3, v1, v3, s[4:5]
	v_add_f32_e32 v2, v2, v3
	v_mul_f32_e32 v3, 0.5, v40
	ds_bpermute_b32 v4, v163, v3
	v_mul_f32_e32 v2, v66, v2
	v_readlane_b32 s3, v252, 63
	s_add_u32 s0, s2, s0
	ds_write2_b32 v239, v0, v2 offset0:8 offset1:10
	v_add_f32_e32 v0, v39, v38
	v_fma_f32 v2, 0.5, v40, v41
	s_addc_u32 s1, s3, 0
	v_mov_b32_e32 v189, v97
	v_add_f32_e32 v5, v0, v2
	s_waitcnt lgkmcnt(1)
	v_cndmask_b32_e64 v6, v4, v1, s[4:5]
	v_lshl_add_u64 v[0:1], s[0:1], 0, v[188:189]
	s_mov_b64 s[0:1], 0x5200000
	v_lshl_add_u64 v[0:1], v[0:1], 0, s[0:1]
	v_mov_b32_e32 v191, v97
	v_lshl_add_u64 v[156:157], v[0:1], 0, v[190:191]
	v_mov_b32_e32 v193, v97
	v_lshl_add_u64 v[158:159], v[0:1], 0, v[192:193]
	global_load_dwordx2 v[0:1], v[156:157], off
	global_load_dwordx2 v[2:3], v[156:157], off offset:16
	global_load_dwordx2 v[132:133], v[156:157], off offset:32
	global_load_dwordx2 v[134:135], v[156:157], off offset:48
	global_load_dwordx2 v[16:17], v[158:159], off
	global_load_dwordx2 v[18:19], v[158:159], off offset:16
	global_load_dwordx2 v[136:137], v[158:159], off offset:32
	global_load_dwordx2 v[138:139], v[158:159], off offset:48
	global_load_dwordx2 v[140:141], v[156:157], off offset:64
	global_load_dwordx2 v[142:143], v[156:157], off offset:80
	global_load_dwordx2 v[144:145], v[156:157], off offset:96
	global_load_dwordx2 v[146:147], v[156:157], off offset:112
	global_load_dwordx2 v[148:149], v[158:159], off offset:64
	global_load_dwordx2 v[150:151], v[158:159], off offset:80
	global_load_dwordx2 v[152:153], v[158:159], off offset:96
	global_load_dwordx2 v[154:155], v[158:159], off offset:112
	v_add_f32_e32 v5, v5, v6
	v_mul_f32_e32 v6, 0.5, v68
	ds_bpermute_b32 v6, v163, v6
	v_add_f32_e32 v7, v67, v43
	v_fma_f32 v8, 0.5, v68, v69
	v_add_f32_e32 v7, v7, v8
	v_mul_f32_e32 v5, v66, v5
	s_waitcnt lgkmcnt(0)
	v_cndmask_b32_e64 v4, v6, v4, s[4:5]
	v_add_f32_e32 v4, v7, v4
	v_mul_f32_e32 v7, 0.5, v45
	ds_bpermute_b32 v7, v163, v7
	v_mul_f32_e32 v4, v66, v4
	ds_write2_b32 v239, v5, v4 offset0:12 offset1:14
	v_add_f32_e32 v4, v44, v42
	v_fma_f32 v5, 0.5, v45, v46
	v_add_f32_e32 v4, v4, v5
	s_waitcnt lgkmcnt(1)
	v_cndmask_b32_e64 v5, v7, v6, s[4:5]
	v_add_f32_e32 v4, v4, v5
	v_mul_f32_e32 v5, 0.5, v71
	ds_bpermute_b32 v5, v163, v5
	v_add_f32_e32 v6, v70, v47
	v_fma_f32 v8, 0.5, v71, v72
	v_add_f32_e32 v6, v6, v8
	v_mul_f32_e32 v4, v66, v4
	s_waitcnt lgkmcnt(0)
	v_cndmask_b32_e64 v7, v5, v7, s[4:5]
	v_add_f32_e32 v6, v6, v7
	v_mul_f32_e32 v7, 0.5, v75
	ds_bpermute_b32 v7, v163, v7
	v_mul_f32_e32 v6, v66, v6
	ds_write2_b32 v239, v4, v6 offset0:16 offset1:18
	v_add_f32_e32 v4, v74, v73
	v_fma_f32 v6, 0.5, v75, v76
	v_add_f32_e32 v4, v4, v6
	s_waitcnt lgkmcnt(1)
	v_cndmask_b32_e64 v5, v7, v5, s[4:5]
	v_add_f32_e32 v4, v4, v5
	v_mul_f32_e32 v5, 0.5, v79
	ds_bpermute_b32 v5, v163, v5
	v_add_f32_e32 v6, v78, v77
	v_fma_f32 v8, 0.5, v79, v80
	v_add_f32_e32 v6, v6, v8
	v_mul_f32_e32 v4, v66, v4
	s_waitcnt lgkmcnt(0)
	v_cndmask_b32_e64 v7, v5, v7, s[4:5]
	v_add_f32_e32 v6, v6, v7
	v_mul_f32_e32 v7, 0.5, v83
	ds_bpermute_b32 v7, v163, v7
	v_mul_f32_e32 v6, v66, v6
	ds_write2_b32 v239, v4, v6 offset0:20 offset1:22
	v_add_f32_e32 v4, v82, v81
	v_fma_f32 v6, 0.5, v83, v84
	v_add_f32_e32 v4, v4, v6
	s_waitcnt lgkmcnt(1)
	v_cndmask_b32_e64 v5, v7, v5, s[4:5]
	v_add_f32_e32 v4, v4, v5
	v_mul_f32_e32 v5, 0.5, v87
	ds_bpermute_b32 v5, v163, v5
	v_add_f32_e32 v6, v86, v85
	v_fma_f32 v8, 0.5, v87, v88
	v_add_f32_e32 v6, v6, v8
	v_mul_f32_e32 v4, v66, v4
	s_waitcnt lgkmcnt(0)
	v_cndmask_b32_e64 v7, v5, v7, s[4:5]
	v_add_f32_e32 v6, v6, v7
	v_mul_f32_e32 v7, 0.5, v91
	ds_bpermute_b32 v7, v163, v7
	v_mul_f32_e32 v6, v66, v6
	ds_write2_b32 v239, v4, v6 offset0:24 offset1:26
	v_add_f32_e32 v4, v90, v89
	v_fma_f32 v6, 0.5, v91, v92
	v_add_f32_e32 v4, v4, v6
	s_waitcnt lgkmcnt(1)
	v_cndmask_b32_e64 v5, v7, v5, s[4:5]
	v_add_f32_e32 v4, v4, v5
	v_mul_f32_e32 v5, 0.5, v95
	ds_bpermute_b32 v5, v163, v5
	v_add_f32_e32 v6, v94, v93
	v_fma_f32 v8, 0.5, v95, v130
	v_add_f32_e32 v6, v6, v8
	v_mul_f32_e32 v4, v66, v4
	s_waitcnt lgkmcnt(0)
	v_cndmask_b32_e64 v5, v5, v7, s[4:5]
	v_add_f32_e32 v5, v6, v5
	v_mul_f32_e32 v5, v66, v5
	ds_write2_b32 v239, v4, v5 offset0:28 offset1:30
	v_cvt_pk_bf16_f32 v20, v65, v64
	v_cvt_pk_bf16_f32 v21, v49, v48
	v_cvt_pk_bf16_f32 v22, v51, v50
	v_cvt_pk_bf16_f32 v23, v53, v52
	v_cvt_pk_bf16_f32 v48, v55, v54
	v_cvt_pk_bf16_f32 v49, v57, v56
	s_waitcnt vmcnt(14)
	v_mfma_f32_32x32x16_bf16 v[0:15], v[0:3], v[20:23], 0
	v_cvt_pk_bf16_f32 v50, v59, v58
	v_cvt_pk_bf16_f32 v51, v61, v60
	s_waitcnt vmcnt(10)
	v_mfma_f32_32x32x16_bf16 v[16:31], v[16:19], v[20:23], 0
	v_mfma_f32_32x32x16_bf16 v[0:15], v[132:135], v[48:51], v[0:15]
	s_waitcnt vmcnt(8)
	v_mfma_f32_32x32x16_bf16 v[16:31], v[136:139], v[48:51], v[16:31]
	v_cvt_pk_bf16_f32 v48, v63, v62
	v_cvt_pk_bf16_f32 v49, v33, v32
	v_cvt_pk_bf16_f32 v50, v35, v34
	v_cvt_pk_bf16_f32 v51, v37, v36
	v_cvt_pk_bf16_f32 v32, v39, v38
	v_cvt_pk_bf16_f32 v33, v41, v40
	v_cvt_pk_bf16_f32 v34, v67, v43
	s_waitcnt vmcnt(6)
	v_mfma_f32_32x32x16_bf16 v[0:15], v[140:143], v[48:51], v[0:15]
	v_cvt_pk_bf16_f32 v35, v69, v68
	s_waitcnt vmcnt(2)
	v_mfma_f32_32x32x16_bf16 v[16:31], v[148:151], v[48:51], v[16:31]
	v_mfma_f32_32x32x16_bf16 v[0:15], v[144:147], v[32:35], v[0:15]
	s_waitcnt vmcnt(0)
	v_mfma_f32_32x32x16_bf16 v[16:31], v[152:155], v[32:35], v[16:31]
	global_load_dwordx2 v[32:33], v[156:157], off offset:128
	global_load_dwordx2 v[34:35], v[156:157], off offset:144
	global_load_dwordx2 v[36:37], v[158:159], off offset:128
	global_load_dwordx2 v[38:39], v[158:159], off offset:144
	global_load_dwordx2 v[48:49], v[156:157], off offset:160
	global_load_dwordx2 v[50:51], v[156:157], off offset:176
	global_load_dwordx2 v[52:53], v[158:159], off offset:160
	global_load_dwordx2 v[54:55], v[158:159], off offset:176
	global_load_dwordx2 v[56:57], v[156:157], off offset:192
	global_load_dwordx2 v[58:59], v[156:157], off offset:208
	global_load_dwordx2 v[60:61], v[158:159], off offset:192
	global_load_dwordx2 v[62:63], v[158:159], off offset:208
	global_load_dwordx2 v[132:133], v[156:157], off offset:224
	global_load_dwordx2 v[134:135], v[156:157], off offset:240
	global_load_dwordx2 v[136:137], v[158:159], off offset:224
	global_load_dwordx2 v[138:139], v[158:159], off offset:240
	v_cvt_pk_bf16_f32 v40, v44, v42
	v_cvt_pk_bf16_f32 v41, v46, v45
	v_cvt_pk_bf16_f32 v42, v70, v47
	v_cvt_pk_bf16_f32 v43, v72, v71
	v_readlane_b32 s0, v251, 44
	v_readlane_b32 s1, v251, 45
	s_waitcnt vmcnt(14)
	v_mfma_f32_32x32x16_bf16 v[0:15], v[32:35], v[40:43], v[0:15]
	v_cvt_pk_bf16_f32 v32, v74, v73
	v_cvt_pk_bf16_f32 v33, v76, v75
	v_cvt_pk_bf16_f32 v34, v78, v77
	v_cvt_pk_bf16_f32 v35, v80, v79
	s_mov_b64 s[14:15], -1
	s_mov_b64 s[12:13], -1
	s_waitcnt vmcnt(12)
	v_mfma_f32_32x32x16_bf16 v[16:31], v[36:39], v[40:43], v[16:31]
	s_waitcnt vmcnt(10)
	v_mfma_f32_32x32x16_bf16 v[0:15], v[48:51], v[32:35], v[0:15]
	s_waitcnt vmcnt(8)
	v_mfma_f32_32x32x16_bf16 v[16:31], v[52:55], v[32:35], v[16:31]
	v_cvt_pk_bf16_f32 v32, v82, v81
	v_cvt_pk_bf16_f32 v33, v84, v83
	v_cvt_pk_bf16_f32 v34, v86, v85
	v_cvt_pk_bf16_f32 v35, v88, v87
	s_waitcnt vmcnt(6)
	s_nop 0
	v_mfma_f32_32x32x16_bf16 v[0:15], v[56:59], v[32:35], v[0:15]
	s_waitcnt vmcnt(4)
	v_mfma_f32_32x32x16_bf16 v[16:31], v[60:63], v[32:35], v[16:31]
	v_cvt_pk_bf16_f32 v32, v90, v89
	v_cvt_pk_bf16_f32 v33, v92, v91
	v_cvt_pk_bf16_f32 v34, v94, v93
	v_cvt_pk_bf16_f32 v35, v130, v95
	s_waitcnt vmcnt(2)
	s_nop 0
	v_mfma_f32_32x32x16_bf16 v[0:15], v[132:135], v[32:35], v[0:15]
	s_waitcnt vmcnt(0)
	v_mfma_f32_32x32x16_bf16 v[16:31], v[136:139], v[32:35], v[16:31]
	v_mul_f32_e32 v32, v162, v66
	s_nop 8
	v_mul_f32_e32 v0, v32, v0
	v_mul_f32_e32 v1, v32, v1
	ds_write2st64_b32 v173, v0, v1 offset1:1
	v_mul_f32_e32 v16, v32, v16
	v_mul_f32_e32 v0, v32, v17
	ds_write2st64_b32 v173, v16, v0 offset0:16 offset1:17
	v_mul_f32_e32 v0, v32, v2
	v_mul_f32_e32 v2, v32, v3
	v_mul_f32_e32 v1, v32, v18
	ds_write2st64_b32 v173, v0, v2 offset0:2 offset1:3
	v_mul_f32_e32 v0, v32, v19
	ds_write2st64_b32 v173, v1, v0 offset0:18 offset1:19
	v_mul_f32_e32 v0, v32, v4
	v_mul_f32_e32 v2, v32, v5
	v_mul_f32_e32 v1, v32, v20
	ds_write2st64_b32 v173, v0, v2 offset0:4 offset1:5
	v_mul_f32_e32 v0, v32, v21
	ds_write2st64_b32 v173, v1, v0 offset0:20 offset1:21
	v_mul_f32_e32 v0, v32, v6
	v_mul_f32_e32 v2, v32, v7
	v_mul_f32_e32 v1, v32, v22
	ds_write2st64_b32 v173, v0, v2 offset0:6 offset1:7
	v_mul_f32_e32 v0, v32, v23
	ds_write2st64_b32 v173, v1, v0 offset0:22 offset1:23
	v_mul_f32_e32 v0, v32, v8
	v_mul_f32_e32 v2, v32, v9
	v_mul_f32_e32 v1, v32, v24
	ds_write2st64_b32 v173, v0, v2 offset0:8 offset1:9
	v_mul_f32_e32 v0, v32, v25
	ds_write2st64_b32 v173, v1, v0 offset0:24 offset1:25
	v_mul_f32_e32 v0, v32, v10
	v_mul_f32_e32 v2, v32, v11
	v_mul_f32_e32 v1, v32, v26
	ds_write2st64_b32 v173, v0, v2 offset0:10 offset1:11
	v_mul_f32_e32 v0, v32, v27
	ds_write2st64_b32 v173, v1, v0 offset0:26 offset1:27
	v_mul_f32_e32 v0, v32, v12
	v_mul_f32_e32 v2, v32, v13
	v_mul_f32_e32 v1, v32, v28
	ds_write2st64_b32 v173, v0, v2 offset0:12 offset1:13
	v_mul_f32_e32 v0, v32, v29
	ds_write2st64_b32 v173, v1, v0 offset0:28 offset1:29
	v_mul_f32_e32 v0, v32, v14
	v_mul_f32_e32 v2, v32, v15
	v_mul_f32_e32 v1, v32, v30
	ds_write2st64_b32 v173, v0, v2 offset0:14 offset1:15
	v_mul_f32_e32 v0, v32, v31
	ds_write2st64_b32 v173, v1, v0 offset0:30 offset1:31
	s_waitcnt lgkmcnt(0)
	s_barrier
	s_add_i32 s51, s50, -2
	s_lshl_b32 s16, 1, s50
	s_lshr_b32 s17, s16, 1
	s_or_b32 s16, s16, s17
	s_or_b32 s16, s16, 1
	s_bcnt1_i32_b32 s17, s16
	s_sub_i32 s17, 8, s17
	s_max_i32 s18, s51, 0
	v_lshl_add_u32 v134, v177, 2, v240
	ds_read_b128 v[80:83], v134
	ds_read_b128 v[84:87], v134 offset:9216
	ds_read_b128 v[88:91], v134 offset:18432
	ds_read_b128 v[92:95], v134 offset:27648
	ds_read_b128 v[32:35], v240
	ds_read_b128 v[36:39], v240 offset:9216
	ds_read_b128 v[40:43], v240 offset:18432
	ds_read_b128 v[44:47], v240 offset:27648
	ds_read_b128 v[48:51], v240 offset:16
	ds_read_b128 v[52:55], v240 offset:9232
	ds_read_b128 v[56:59], v240 offset:18448
	ds_read_b128 v[60:63], v240 offset:27664
	s_waitcnt lgkmcnt(8)
	v_pk_add_f32 v[80:81], v[80:81], v[84:85]
	v_pk_add_f32 v[82:83], v[82:83], v[86:87]
	v_pk_add_f32 v[88:89], v[88:89], v[92:93]
	v_pk_add_f32 v[90:91], v[90:91], v[94:95]
	v_pk_add_f32 v[80:81], v[80:81], v[88:89]
	v_pk_add_f32 v[82:83], v[82:83], v[90:91]
	ds_read_b128 v[64:67], v240 offset:32
	ds_read_b128 v[68:71], v240 offset:9248
	ds_read_b128 v[72:75], v240 offset:18464
	ds_read_b128 v[76:79], v240 offset:27680
	v_add_u32_e32 v140, -1, v177
	v_add_u32_e32 v141, 0, v177
	v_add_u32_e32 v142, 1, v177
	v_add_u32_e32 v143, 2, v177
	v_cmp_gt_u32_e64 s[20:21], s18, v140
	v_cmp_gt_u32_e64 s[22:23], s18, v141
	v_cmp_gt_u32_e64 s[24:25], s18, v142
	v_cmp_gt_u32_e64 s[26:27], s18, v143
	v_mov_b32_e32 v136, 0
	v_mov_b32_e32 v137, 0
	v_mov_b32_e32 v138, 0
	v_mov_b32_e32 v139, 0
	v_cndmask_b32_e64 v80, -1, v80, s[20:21]
	v_cndmask_b32_e64 v81, -1, v81, s[22:23]
	v_cndmask_b32_e64 v82, -1, v82, s[24:25]
	v_cndmask_b32_e64 v83, -1, v83, s[26:27]
	v_add_u32_e32 v84, -1, v80
	v_add_u32_e32 v85, -1, v81
	v_add_u32_e32 v86, -1, v82
	v_add_u32_e32 v87, -1, v83
	s_waitcnt lgkmcnt(8)
	v_pk_add_f32 v[32:33], v[32:33], v[36:37]
	v_pk_add_f32 v[34:35], v[34:35], v[38:39]
	v_pk_add_f32 v[40:41], v[40:41], v[44:45]
	v_pk_add_f32 v[42:43], v[42:43], v[46:47]
	v_pk_add_f32 v[0:1], v[32:33], v[40:41]
	v_pk_add_f32 v[2:3], v[34:35], v[42:43]
	ds_read_b128 v[32:35], v240 offset:48
	ds_read_b128 v[36:39], v240 offset:9264
	ds_read_b128 v[40:43], v240 offset:18480
	ds_read_b128 v[44:47], v240 offset:27696
	v_cmp_le_u32_e64 s[30:31], 4, v177
	s_cmp_gt_i32 s18, 0
	s_cselect_b64 s[28:29], -1, 0
	v_cndmask_b32_e64 v1, -1, v1, s[28:29]
	s_cmp_gt_i32 s18, 1
	s_cselect_b64 s[28:29], -1, 0
	v_cndmask_b32_e64 v2, -1, v2, s[28:29]
	s_cmp_gt_i32 s18, 2
	s_cselect_b64 s[28:29], -1, 0
	v_cndmask_b32_e64 v3, -1, v3, s[28:29]
	v_cndmask_b32_e64 v92, v80, v84, s[30:31]
	v_cndmask_b32_e64 v93, v81, v85, s[30:31]
	v_cndmask_b32_e64 v94, v82, v86, s[30:31]
	v_cndmask_b32_e64 v95, v83, v87, s[30:31]
	v_cmp_gt_i32_e64 s[38:39], v1, v92
	v_cmp_gt_i32_e64 s[40:41], v1, v93
	v_cmp_gt_i32_e64 s[42:43], v1, v86
	v_cmp_gt_i32_e64 s[44:45], v1, v87
	v_addc_co_u32_e64 v136, s[36:37], 0, v136, s[38:39]
	v_addc_co_u32_e64 v137, s[36:37], 0, v137, s[40:41]
	v_addc_co_u32_e64 v138, s[36:37], 0, v138, s[42:43]
	v_addc_co_u32_e64 v139, s[36:37], 0, v139, s[44:45]
	v_cmp_gt_i32_e64 s[38:39], v2, v92
	v_cmp_gt_i32_e64 s[40:41], v2, v93
	v_cmp_gt_i32_e64 s[42:43], v2, v94
	v_cmp_gt_i32_e64 s[44:45], v2, v87
	v_addc_co_u32_e64 v136, s[36:37], 0, v136, s[38:39]
	v_addc_co_u32_e64 v137, s[36:37], 0, v137, s[40:41]
	v_addc_co_u32_e64 v138, s[36:37], 0, v138, s[42:43]
	v_addc_co_u32_e64 v139, s[36:37], 0, v139, s[44:45]
	v_cmp_gt_i32_e64 s[38:39], v3, v92
	v_cmp_gt_i32_e64 s[40:41], v3, v93
	v_cmp_gt_i32_e64 s[42:43], v3, v94
	v_cmp_gt_i32_e64 s[44:45], v3, v95
	v_addc_co_u32_e64 v136, s[36:37], 0, v136, s[38:39]
	v_addc_co_u32_e64 v137, s[36:37], 0, v137, s[40:41]
	v_addc_co_u32_e64 v138, s[36:37], 0, v138, s[42:43]
	v_addc_co_u32_e64 v139, s[36:37], 0, v139, s[44:45]
	s_waitcnt lgkmcnt(8)
	v_pk_add_f32 v[48:49], v[48:49], v[52:53]
	v_pk_add_f32 v[50:51], v[50:51], v[54:55]
	v_pk_add_f32 v[56:57], v[56:57], v[60:61]
	v_pk_add_f32 v[58:59], v[58:59], v[62:63]
	v_pk_add_f32 v[4:5], v[48:49], v[56:57]
	v_pk_add_f32 v[6:7], v[50:51], v[58:59]
	ds_read_b128 v[48:51], v240 offset:64
	ds_read_b128 v[52:55], v240 offset:9280
	ds_read_b128 v[56:59], v240 offset:18496
	ds_read_b128 v[60:63], v240 offset:27712
	v_cmp_le_u32_e64 s[30:31], 8, v177
	s_cmp_gt_i32 s18, 3
	s_cselect_b64 s[28:29], -1, 0
	v_cndmask_b32_e64 v4, -1, v4, s[28:29]
	s_cmp_gt_i32 s18, 4
	s_cselect_b64 s[28:29], -1, 0
	v_cndmask_b32_e64 v5, -1, v5, s[28:29]
	s_cmp_gt_i32 s18, 5
	s_cselect_b64 s[28:29], -1, 0
	v_cndmask_b32_e64 v6, -1, v6, s[28:29]
	s_cmp_gt_i32 s18, 6
	s_cselect_b64 s[28:29], -1, 0
	v_cndmask_b32_e64 v7, -1, v7, s[28:29]
	v_cndmask_b32_e64 v88, v80, v84, s[30:31]
	v_cndmask_b32_e64 v89, v81, v85, s[30:31]
	v_cndmask_b32_e64 v90, v82, v86, s[30:31]
	v_cndmask_b32_e64 v91, v83, v87, s[30:31]
	v_cmp_gt_i32_e64 s[38:39], v4, v88
	v_cmp_gt_i32_e64 s[40:41], v4, v93
	v_cmp_gt_i32_e64 s[42:43], v4, v94
	v_cmp_gt_i32_e64 s[44:45], v4, v95
	v_addc_co_u32_e64 v136, s[36:37], 0, v136, s[38:39]
	v_addc_co_u32_e64 v137, s[36:37], 0, v137, s[40:41]
	v_addc_co_u32_e64 v138, s[36:37], 0, v138, s[42:43]
	v_addc_co_u32_e64 v139, s[36:37], 0, v139, s[44:45]
	v_cmp_gt_i32_e64 s[38:39], v5, v88
	v_cmp_gt_i32_e64 s[40:41], v5, v89
	v_cmp_gt_i32_e64 s[42:43], v5, v94
	v_cmp_gt_i32_e64 s[44:45], v5, v95
	v_addc_co_u32_e64 v136, s[36:37], 0, v136, s[38:39]
	v_addc_co_u32_e64 v137, s[36:37], 0, v137, s[40:41]
	v_addc_co_u32_e64 v138, s[36:37], 0, v138, s[42:43]
	v_addc_co_u32_e64 v139, s[36:37], 0, v139, s[44:45]
	v_cmp_gt_i32_e64 s[38:39], v6, v88
	v_cmp_gt_i32_e64 s[40:41], v6, v89
	v_cmp_gt_i32_e64 s[42:43], v6, v90
	v_cmp_gt_i32_e64 s[44:45], v6, v95
	v_addc_co_u32_e64 v136, s[36:37], 0, v136, s[38:39]
	v_addc_co_u32_e64 v137, s[36:37], 0, v137, s[40:41]
	v_addc_co_u32_e64 v138, s[36:37], 0, v138, s[42:43]
	v_addc_co_u32_e64 v139, s[36:37], 0, v139, s[44:45]
	v_cmp_gt_i32_e64 s[38:39], v7, v88
	v_cmp_gt_i32_e64 s[40:41], v7, v89
	v_cmp_gt_i32_e64 s[42:43], v7, v90
	v_cmp_gt_i32_e64 s[44:45], v7, v91
	v_addc_co_u32_e64 v136, s[36:37], 0, v136, s[38:39]
	v_addc_co_u32_e64 v137, s[36:37], 0, v137, s[40:41]
	v_addc_co_u32_e64 v138, s[36:37], 0, v138, s[42:43]
	v_addc_co_u32_e64 v139, s[36:37], 0, v139, s[44:45]
	s_waitcnt lgkmcnt(8)
	v_pk_add_f32 v[64:65], v[64:65], v[68:69]
	v_pk_add_f32 v[66:67], v[66:67], v[70:71]
	v_pk_add_f32 v[72:73], v[72:73], v[76:77]
	v_pk_add_f32 v[74:75], v[74:75], v[78:79]
	v_pk_add_f32 v[8:9], v[64:65], v[72:73]
	v_pk_add_f32 v[10:11], v[66:67], v[74:75]
	ds_read_b128 v[64:67], v240 offset:80
	ds_read_b128 v[68:71], v240 offset:9296
	ds_read_b128 v[72:75], v240 offset:18512
	ds_read_b128 v[76:79], v240 offset:27728
	v_cmp_le_u32_e64 s[30:31], 12, v177
	s_cmp_gt_i32 s18, 7
	s_cselect_b64 s[28:29], -1, 0
	v_cndmask_b32_e64 v8, -1, v8, s[28:29]
	s_cmp_gt_i32 s18, 8
	s_cselect_b64 s[28:29], -1, 0
	v_cndmask_b32_e64 v9, -1, v9, s[28:29]
	s_cmp_gt_i32 s18, 9
	s_cselect_b64 s[28:29], -1, 0
	v_cndmask_b32_e64 v10, -1, v10, s[28:29]
	s_cmp_gt_i32 s18, 10
	s_cselect_b64 s[28:29], -1, 0
	v_cndmask_b32_e64 v11, -1, v11, s[28:29]
	v_cndmask_b32_e64 v92, v80, v84, s[30:31]
	v_cndmask_b32_e64 v93, v81, v85, s[30:31]
	v_cndmask_b32_e64 v94, v82, v86, s[30:31]
	v_cndmask_b32_e64 v95, v83, v87, s[30:31]
	v_cmp_gt_i32_e64 s[38:39], v8, v92
	v_cmp_gt_i32_e64 s[40:41], v8, v89
	v_cmp_gt_i32_e64 s[42:43], v8, v90
	v_cmp_gt_i32_e64 s[44:45], v8, v91
	v_addc_co_u32_e64 v136, s[36:37], 0, v136, s[38:39]
	v_addc_co_u32_e64 v137, s[36:37], 0, v137, s[40:41]
	v_addc_co_u32_e64 v138, s[36:37], 0, v138, s[42:43]
	v_addc_co_u32_e64 v139, s[36:37], 0, v139, s[44:45]
	v_cmp_gt_i32_e64 s[38:39], v9, v92
	v_cmp_gt_i32_e64 s[40:41], v9, v93
	v_cmp_gt_i32_e64 s[42:43], v9, v90
	v_cmp_gt_i32_e64 s[44:45], v9, v91
	v_addc_co_u32_e64 v136, s[36:37], 0, v136, s[38:39]
	v_addc_co_u32_e64 v137, s[36:37], 0, v137, s[40:41]
	v_addc_co_u32_e64 v138, s[36:37], 0, v138, s[42:43]
	v_addc_co_u32_e64 v139, s[36:37], 0, v139, s[44:45]
	v_cmp_gt_i32_e64 s[38:39], v10, v92
	v_cmp_gt_i32_e64 s[40:41], v10, v93
	v_cmp_gt_i32_e64 s[42:43], v10, v94
	v_cmp_gt_i32_e64 s[44:45], v10, v91
	v_addc_co_u32_e64 v136, s[36:37], 0, v136, s[38:39]
	v_addc_co_u32_e64 v137, s[36:37], 0, v137, s[40:41]
	v_addc_co_u32_e64 v138, s[36:37], 0, v138, s[42:43]
	v_addc_co_u32_e64 v139, s[36:37], 0, v139, s[44:45]
	v_cmp_gt_i32_e64 s[38:39], v11, v92
	v_cmp_gt_i32_e64 s[40:41], v11, v93
	v_cmp_gt_i32_e64 s[42:43], v11, v94
	v_cmp_gt_i32_e64 s[44:45], v11, v95
	v_addc_co_u32_e64 v136, s[36:37], 0, v136, s[38:39]
	v_addc_co_u32_e64 v137, s[36:37], 0, v137, s[40:41]
	v_addc_co_u32_e64 v138, s[36:37], 0, v138, s[42:43]
	v_addc_co_u32_e64 v139, s[36:37], 0, v139, s[44:45]
	s_waitcnt lgkmcnt(8)
	v_pk_add_f32 v[32:33], v[32:33], v[36:37]
	v_pk_add_f32 v[34:35], v[34:35], v[38:39]
	v_pk_add_f32 v[40:41], v[40:41], v[44:45]
	v_pk_add_f32 v[42:43], v[42:43], v[46:47]
	v_pk_add_f32 v[12:13], v[32:33], v[40:41]
	v_pk_add_f32 v[14:15], v[34:35], v[42:43]
	ds_read_b128 v[32:35], v240 offset:96
	ds_read_b128 v[36:39], v240 offset:9312
	ds_read_b128 v[40:43], v240 offset:18528
	ds_read_b128 v[44:47], v240 offset:27744
	v_cmp_le_u32_e64 s[30:31], 16, v177
	s_cmp_gt_i32 s18, 11
	s_cselect_b64 s[28:29], -1, 0
	v_cndmask_b32_e64 v12, -1, v12, s[28:29]
	s_cmp_gt_i32 s18, 12
	s_cselect_b64 s[28:29], -1, 0
	v_cndmask_b32_e64 v13, -1, v13, s[28:29]
	s_cmp_gt_i32 s18, 13
	s_cselect_b64 s[28:29], -1, 0
	v_cndmask_b32_e64 v14, -1, v14, s[28:29]
	s_cmp_gt_i32 s18, 14
	s_cselect_b64 s[28:29], -1, 0
	v_cndmask_b32_e64 v15, -1, v15, s[28:29]
	v_cndmask_b32_e64 v88, v80, v84, s[30:31]
	v_cndmask_b32_e64 v89, v81, v85, s[30:31]
	v_cndmask_b32_e64 v90, v82, v86, s[30:31]
	v_cndmask_b32_e64 v91, v83, v87, s[30:31]
	v_cmp_gt_i32_e64 s[38:39], v12, v88
	v_cmp_gt_i32_e64 s[40:41], v12, v93
	v_cmp_gt_i32_e64 s[42:43], v12, v94
	v_cmp_gt_i32_e64 s[44:45], v12, v95
	v_addc_co_u32_e64 v136, s[36:37], 0, v136, s[38:39]
	v_addc_co_u32_e64 v137, s[36:37], 0, v137, s[40:41]
	v_addc_co_u32_e64 v138, s[36:37], 0, v138, s[42:43]
	v_addc_co_u32_e64 v139, s[36:37], 0, v139, s[44:45]
	v_cmp_gt_i32_e64 s[38:39], v13, v88
	v_cmp_gt_i32_e64 s[40:41], v13, v89
	v_cmp_gt_i32_e64 s[42:43], v13, v94
	v_cmp_gt_i32_e64 s[44:45], v13, v95
	v_addc_co_u32_e64 v136, s[36:37], 0, v136, s[38:39]
	v_addc_co_u32_e64 v137, s[36:37], 0, v137, s[40:41]
	v_addc_co_u32_e64 v138, s[36:37], 0, v138, s[42:43]
	v_addc_co_u32_e64 v139, s[36:37], 0, v139, s[44:45]
	v_cmp_gt_i32_e64 s[38:39], v14, v88
	v_cmp_gt_i32_e64 s[40:41], v14, v89
	v_cmp_gt_i32_e64 s[42:43], v14, v90
	v_cmp_gt_i32_e64 s[44:45], v14, v95
	v_addc_co_u32_e64 v136, s[36:37], 0, v136, s[38:39]
	v_addc_co_u32_e64 v137, s[36:37], 0, v137, s[40:41]
	v_addc_co_u32_e64 v138, s[36:37], 0, v138, s[42:43]
	v_addc_co_u32_e64 v139, s[36:37], 0, v139, s[44:45]
	v_cmp_gt_i32_e64 s[38:39], v15, v88
	v_cmp_gt_i32_e64 s[40:41], v15, v89
	v_cmp_gt_i32_e64 s[42:43], v15, v90
	v_cmp_gt_i32_e64 s[44:45], v15, v91
	v_addc_co_u32_e64 v136, s[36:37], 0, v136, s[38:39]
	v_addc_co_u32_e64 v137, s[36:37], 0, v137, s[40:41]
	v_addc_co_u32_e64 v138, s[36:37], 0, v138, s[42:43]
	v_addc_co_u32_e64 v139, s[36:37], 0, v139, s[44:45]
	s_waitcnt lgkmcnt(8)
	v_pk_add_f32 v[48:49], v[48:49], v[52:53]
	v_pk_add_f32 v[50:51], v[50:51], v[54:55]
	v_pk_add_f32 v[56:57], v[56:57], v[60:61]
	v_pk_add_f32 v[58:59], v[58:59], v[62:63]
	v_pk_add_f32 v[16:17], v[48:49], v[56:57]
	v_pk_add_f32 v[18:19], v[50:51], v[58:59]
	ds_read_b128 v[48:51], v240 offset:112
	ds_read_b128 v[52:55], v240 offset:9328
	ds_read_b128 v[56:59], v240 offset:18544
	ds_read_b128 v[60:63], v240 offset:27760
	v_cmp_le_u32_e64 s[30:31], 20, v177
	s_cmp_gt_i32 s18, 15
	s_cselect_b64 s[28:29], -1, 0
	v_cndmask_b32_e64 v16, -1, v16, s[28:29]
	s_cmp_gt_i32 s18, 16
	s_cselect_b64 s[28:29], -1, 0
	v_cndmask_b32_e64 v17, -1, v17, s[28:29]
	s_cmp_gt_i32 s18, 17
	s_cselect_b64 s[28:29], -1, 0
	v_cndmask_b32_e64 v18, -1, v18, s[28:29]
	s_cmp_gt_i32 s18, 18
	s_cselect_b64 s[28:29], -1, 0
	v_cndmask_b32_e64 v19, -1, v19, s[28:29]
	v_cndmask_b32_e64 v92, v80, v84, s[30:31]
	v_cndmask_b32_e64 v93, v81, v85, s[30:31]
	v_cndmask_b32_e64 v94, v82, v86, s[30:31]
	v_cndmask_b32_e64 v95, v83, v87, s[30:31]
	v_cmp_gt_i32_e64 s[38:39], v16, v92
	v_cmp_gt_i32_e64 s[40:41], v16, v89
	v_cmp_gt_i32_e64 s[42:43], v16, v90
	v_cmp_gt_i32_e64 s[44:45], v16, v91
	v_addc_co_u32_e64 v136, s[36:37], 0, v136, s[38:39]
	v_addc_co_u32_e64 v137, s[36:37], 0, v137, s[40:41]
	v_addc_co_u32_e64 v138, s[36:37], 0, v138, s[42:43]
	v_addc_co_u32_e64 v139, s[36:37], 0, v139, s[44:45]
	v_cmp_gt_i32_e64 s[38:39], v17, v92
	v_cmp_gt_i32_e64 s[40:41], v17, v93
	v_cmp_gt_i32_e64 s[42:43], v17, v90
	v_cmp_gt_i32_e64 s[44:45], v17, v91
	v_addc_co_u32_e64 v136, s[36:37], 0, v136, s[38:39]
	v_addc_co_u32_e64 v137, s[36:37], 0, v137, s[40:41]
	v_addc_co_u32_e64 v138, s[36:37], 0, v138, s[42:43]
	v_addc_co_u32_e64 v139, s[36:37], 0, v139, s[44:45]
	v_cmp_gt_i32_e64 s[38:39], v18, v92
	v_cmp_gt_i32_e64 s[40:41], v18, v93
	v_cmp_gt_i32_e64 s[42:43], v18, v94
	v_cmp_gt_i32_e64 s[44:45], v18, v91
	v_addc_co_u32_e64 v136, s[36:37], 0, v136, s[38:39]
	v_addc_co_u32_e64 v137, s[36:37], 0, v137, s[40:41]
	v_addc_co_u32_e64 v138, s[36:37], 0, v138, s[42:43]
	v_addc_co_u32_e64 v139, s[36:37], 0, v139, s[44:45]
	v_cmp_gt_i32_e64 s[38:39], v19, v92
	v_cmp_gt_i32_e64 s[40:41], v19, v93
	v_cmp_gt_i32_e64 s[42:43], v19, v94
	v_cmp_gt_i32_e64 s[44:45], v19, v95
	v_addc_co_u32_e64 v136, s[36:37], 0, v136, s[38:39]
	v_addc_co_u32_e64 v137, s[36:37], 0, v137, s[40:41]
	v_addc_co_u32_e64 v138, s[36:37], 0, v138, s[42:43]
	v_addc_co_u32_e64 v139, s[36:37], 0, v139, s[44:45]
	s_waitcnt lgkmcnt(8)
	v_pk_add_f32 v[64:65], v[64:65], v[68:69]
	v_pk_add_f32 v[66:67], v[66:67], v[70:71]
	v_pk_add_f32 v[72:73], v[72:73], v[76:77]
	v_pk_add_f32 v[74:75], v[74:75], v[78:79]
	v_pk_add_f32 v[20:21], v[64:65], v[72:73]
	v_pk_add_f32 v[22:23], v[66:67], v[74:75]
	v_cmp_le_u32_e64 s[30:31], 24, v177
	s_cmp_gt_i32 s18, 19
	s_cselect_b64 s[28:29], -1, 0
	v_cndmask_b32_e64 v20, -1, v20, s[28:29]
	s_cmp_gt_i32 s18, 20
	s_cselect_b64 s[28:29], -1, 0
	v_cndmask_b32_e64 v21, -1, v21, s[28:29]
	s_cmp_gt_i32 s18, 21
	s_cselect_b64 s[28:29], -1, 0
	v_cndmask_b32_e64 v22, -1, v22, s[28:29]
	s_cmp_gt_i32 s18, 22
	s_cselect_b64 s[28:29], -1, 0
	v_cndmask_b32_e64 v23, -1, v23, s[28:29]
	v_cndmask_b32_e64 v88, v80, v84, s[30:31]
	v_cndmask_b32_e64 v89, v81, v85, s[30:31]
	v_cndmask_b32_e64 v90, v82, v86, s[30:31]
	v_cndmask_b32_e64 v91, v83, v87, s[30:31]
	v_cmp_gt_i32_e64 s[38:39], v20, v88
	v_cmp_gt_i32_e64 s[40:41], v20, v93
	v_cmp_gt_i32_e64 s[42:43], v20, v94
	v_cmp_gt_i32_e64 s[44:45], v20, v95
	v_addc_co_u32_e64 v136, s[36:37], 0, v136, s[38:39]
	v_addc_co_u32_e64 v137, s[36:37], 0, v137, s[40:41]
	v_addc_co_u32_e64 v138, s[36:37], 0, v138, s[42:43]
	v_addc_co_u32_e64 v139, s[36:37], 0, v139, s[44:45]
	v_cmp_gt_i32_e64 s[38:39], v21, v88
	v_cmp_gt_i32_e64 s[40:41], v21, v89
	v_cmp_gt_i32_e64 s[42:43], v21, v94
	v_cmp_gt_i32_e64 s[44:45], v21, v95
	v_addc_co_u32_e64 v136, s[36:37], 0, v136, s[38:39]
	v_addc_co_u32_e64 v137, s[36:37], 0, v137, s[40:41]
	v_addc_co_u32_e64 v138, s[36:37], 0, v138, s[42:43]
	v_addc_co_u32_e64 v139, s[36:37], 0, v139, s[44:45]
	v_cmp_gt_i32_e64 s[38:39], v22, v88
	v_cmp_gt_i32_e64 s[40:41], v22, v89
	v_cmp_gt_i32_e64 s[42:43], v22, v90
	v_cmp_gt_i32_e64 s[44:45], v22, v95
	v_addc_co_u32_e64 v136, s[36:37], 0, v136, s[38:39]
	v_addc_co_u32_e64 v137, s[36:37], 0, v137, s[40:41]
	v_addc_co_u32_e64 v138, s[36:37], 0, v138, s[42:43]
	v_addc_co_u32_e64 v139, s[36:37], 0, v139, s[44:45]
	v_cmp_gt_i32_e64 s[38:39], v23, v88
	v_cmp_gt_i32_e64 s[40:41], v23, v89
	v_cmp_gt_i32_e64 s[42:43], v23, v90
	v_cmp_gt_i32_e64 s[44:45], v23, v91
	v_addc_co_u32_e64 v136, s[36:37], 0, v136, s[38:39]
	v_addc_co_u32_e64 v137, s[36:37], 0, v137, s[40:41]
	v_addc_co_u32_e64 v138, s[36:37], 0, v138, s[42:43]
	v_addc_co_u32_e64 v139, s[36:37], 0, v139, s[44:45]
	s_waitcnt lgkmcnt(4)
	v_pk_add_f32 v[32:33], v[32:33], v[36:37]
	v_pk_add_f32 v[34:35], v[34:35], v[38:39]
	v_pk_add_f32 v[40:41], v[40:41], v[44:45]
	v_pk_add_f32 v[42:43], v[42:43], v[46:47]
	v_pk_add_f32 v[24:25], v[32:33], v[40:41]
	v_pk_add_f32 v[26:27], v[34:35], v[42:43]
	v_cmp_le_u32_e64 s[30:31], 28, v177
	s_cmp_gt_i32 s18, 23
	s_cselect_b64 s[28:29], -1, 0
	v_cndmask_b32_e64 v24, -1, v24, s[28:29]
	s_cmp_gt_i32 s18, 24
	s_cselect_b64 s[28:29], -1, 0
	v_cndmask_b32_e64 v25, -1, v25, s[28:29]
	s_cmp_gt_i32 s18, 25
	s_cselect_b64 s[28:29], -1, 0
	v_cndmask_b32_e64 v26, -1, v26, s[28:29]
	s_cmp_gt_i32 s18, 26
	s_cselect_b64 s[28:29], -1, 0
	v_cndmask_b32_e64 v27, -1, v27, s[28:29]
	v_cndmask_b32_e64 v92, v80, v84, s[30:31]
	v_cndmask_b32_e64 v93, v81, v85, s[30:31]
	v_cndmask_b32_e64 v94, v82, v86, s[30:31]
	v_cndmask_b32_e64 v95, v83, v87, s[30:31]
	v_cmp_gt_i32_e64 s[38:39], v24, v92
	v_cmp_gt_i32_e64 s[40:41], v24, v89
	v_cmp_gt_i32_e64 s[42:43], v24, v90
	v_cmp_gt_i32_e64 s[44:45], v24, v91
	v_addc_co_u32_e64 v136, s[36:37], 0, v136, s[38:39]
	v_addc_co_u32_e64 v137, s[36:37], 0, v137, s[40:41]
	v_addc_co_u32_e64 v138, s[36:37], 0, v138, s[42:43]
	v_addc_co_u32_e64 v139, s[36:37], 0, v139, s[44:45]
	v_cmp_gt_i32_e64 s[38:39], v25, v92
	v_cmp_gt_i32_e64 s[40:41], v25, v93
	v_cmp_gt_i32_e64 s[42:43], v25, v90
	v_cmp_gt_i32_e64 s[44:45], v25, v91
	v_addc_co_u32_e64 v136, s[36:37], 0, v136, s[38:39]
	v_addc_co_u32_e64 v137, s[36:37], 0, v137, s[40:41]
	v_addc_co_u32_e64 v138, s[36:37], 0, v138, s[42:43]
	v_addc_co_u32_e64 v139, s[36:37], 0, v139, s[44:45]
	v_cmp_gt_i32_e64 s[38:39], v26, v92
	v_cmp_gt_i32_e64 s[40:41], v26, v93
	v_cmp_gt_i32_e64 s[42:43], v26, v94
	v_cmp_gt_i32_e64 s[44:45], v26, v91
	v_addc_co_u32_e64 v136, s[36:37], 0, v136, s[38:39]
	v_addc_co_u32_e64 v137, s[36:37], 0, v137, s[40:41]
	v_addc_co_u32_e64 v138, s[36:37], 0, v138, s[42:43]
	v_addc_co_u32_e64 v139, s[36:37], 0, v139, s[44:45]
	v_cmp_gt_i32_e64 s[38:39], v27, v92
	v_cmp_gt_i32_e64 s[40:41], v27, v93
	v_cmp_gt_i32_e64 s[42:43], v27, v94
	v_cmp_gt_i32_e64 s[44:45], v27, v95
	v_addc_co_u32_e64 v136, s[36:37], 0, v136, s[38:39]
	v_addc_co_u32_e64 v137, s[36:37], 0, v137, s[40:41]
	v_addc_co_u32_e64 v138, s[36:37], 0, v138, s[42:43]
	v_addc_co_u32_e64 v139, s[36:37], 0, v139, s[44:45]
	s_waitcnt lgkmcnt(0)
	v_pk_add_f32 v[48:49], v[48:49], v[52:53]
	v_pk_add_f32 v[50:51], v[50:51], v[54:55]
	v_pk_add_f32 v[56:57], v[56:57], v[60:61]
	v_pk_add_f32 v[58:59], v[58:59], v[62:63]
	v_pk_add_f32 v[28:29], v[48:49], v[56:57]
	v_pk_add_f32 v[30:31], v[50:51], v[58:59]
	s_cmp_gt_i32 s18, 27
	s_cselect_b64 s[28:29], -1, 0
	v_cndmask_b32_e64 v28, -1, v28, s[28:29]
	s_cmp_gt_i32 s18, 28
	s_cselect_b64 s[28:29], -1, 0
	v_cndmask_b32_e64 v29, -1, v29, s[28:29]
	v_cmp_gt_i32_e64 s[38:39], v28, v80
	v_cmp_gt_i32_e64 s[40:41], v28, v93
	v_cmp_gt_i32_e64 s[42:43], v28, v94
	v_cmp_gt_i32_e64 s[44:45], v28, v95
	v_addc_co_u32_e64 v136, s[36:37], 0, v136, s[38:39]
	v_addc_co_u32_e64 v137, s[36:37], 0, v137, s[40:41]
	v_addc_co_u32_e64 v138, s[36:37], 0, v138, s[42:43]
	v_addc_co_u32_e64 v139, s[36:37], 0, v139, s[44:45]
	v_cmp_gt_i32_e64 s[38:39], v29, v80
	v_cmp_gt_i32_e64 s[40:41], v29, v81
	v_cmp_gt_i32_e64 s[42:43], v29, v94
	v_cmp_gt_i32_e64 s[44:45], v29, v95
	v_addc_co_u32_e64 v136, s[36:37], 0, v136, s[38:39]
	v_addc_co_u32_e64 v137, s[36:37], 0, v137, s[40:41]
	v_addc_co_u32_e64 v138, s[36:37], 0, v138, s[42:43]
	v_addc_co_u32_e64 v139, s[36:37], 0, v139, s[44:45]
	v_cmp_gt_i32_e64 s[38:39], s17, v136
	v_cmp_gt_i32_e64 s[40:41], s17, v137
	v_cmp_gt_i32_e64 s[42:43], s17, v138
	v_cmp_gt_i32_e64 s[44:45], s17, v139
	s_and_b64 s[38:39], s[38:39], s[20:21]
	s_and_b64 s[40:41], s[40:41], s[22:23]
	s_and_b64 s[42:43], s[42:43], s[24:25]
	s_and_b64 s[44:45], s[44:45], s[26:27]
	v_cndmask_b32_e64 v140, 0, v231, s[38:39]
	v_cndmask_b32_e64 v141, 0, v232, s[40:41]
	v_cndmask_b32_e64 v142, 0, v234, s[42:43]
	v_cndmask_b32_e64 v143, 0, v236, s[44:45]
	v_or3_b32 v140, v140, v141, v142
	v_or_b32_e32 v140, v140, v143
	s_nop 1
	v_or_b32_dpp v141, v140, v140 quad_perm:[1,0,3,2] row_mask:0xf bank_mask:0xf
	s_nop 1
	v_or_b32_dpp v140, v141, v141 quad_perm:[2,3,0,1] row_mask:0xf bank_mask:0xf
	s_nop 1
	v_or_b32_dpp v141, v140, v140 row_half_mirror row_mask:0xf bank_mask:0xf
	v_cmp_eq_u32_e32 vcc, 0, v177
	v_or_b32_e32 v141, s16, v141
	s_and_saveexec_b64 s[0:1], vcc
	s_cbranch_execz .LBB0_398
	ds_write_b32 v179, v141
